# XCD-local barrier at the out-projection -> up-projection seam (per-XCC counter, no L2 write-back) when a runtime placement check shows each blockIdx&7 group sits on one XCC; grid-wide barrier otherwis
# baseline (speedup 1.0000x reference)
_Z9hymba_fwd4Args:
	s_mov_b64 s[84:85], s[0:1]
	s_mov_b32 s78, s2
	s_mov_b64 s[2:3], s[84:85]
	s_load_dwordx2 s[86:87], s[0:1], 0x88
	s_nop 0
	s_load_dword s0, s[0:1], 0x90
	s_load_dwordx2 s[10:11], s[2:3], 0x80
	s_add_u32 s12, s84, 0x88
	v_and_b32_e32 v208, 0x3ff, v0
	s_addc_u32 s13, s85, 0
	v_cmp_gt_u32_e32 vcc, 2, v208
	s_and_saveexec_b64 s[4:5], vcc
	v_lshl_add_u32 v1, v208, 2, 0
	v_add_u32_e32 v1, 0x22400, v1
	v_mov_b32_e32 v2, 0
	ds_write_b32 v1, v2
	s_or_b64 exec, exec, s[4:5]
	s_waitcnt lgkmcnt(0)
	s_barrier
	s_add_u32 s92, s10, 0x1ce00000
	s_getreg_b32 s1, hwreg(HW_REG_XCC_ID, 0, 4)
	s_addc_u32 s93, s11, 0
	s_and_b32 s73, s1, 15
	v_cmp_eq_u32_e64 s[2:3], 0, v208
	s_mov_b64 s[6:7], exec
	s_nop 0
	v_writelane_b32 v254, s2, 0
	s_nop 1
	v_writelane_b32 v254, s3, 1
	s_and_b64 s[2:3], s[6:7], s[2:3]
	s_mov_b64 exec, s[2:3]
	s_cbranch_execz .LBB0_5
	s_mov_b64 s[8:9], exec
	v_mbcnt_lo_u32_b32 v1, s8, 0
	v_mbcnt_hi_u32_b32 v1, s9, v1
	v_cmp_eq_u32_e32 vcc, 0, v1
	s_and_b64 s[2:3], exec, vcc
	s_mov_b64 exec, s[2:3]
	s_cbranch_execz .LBB0_5
	s_lshl_b32 s1, s73, 8
	s_bcnt1_i32_b64 s2, s[8:9]
	v_mov_b32_e32 v1, s1
	v_mov_b32_e32 v2, s2
	global_atomic_add v1, v2, s[92:93] offset:1024
	s_and_b32 s2, s78, 7
	s_lshl_b32 s2, s2, 2
	s_lshl_b32 s3, 1, s73
	v_mov_b32_e32 v3, s2
	v_mov_b32_e32 v4, s3
	global_atomic_or v3, v4, s[92:93]

.LBB0_129:
	s_or_b64 exec, exec, s[6:7]
	s_ashr_i32 s87, s86, 31
	s_ashr_i32 s79, s78, 31
	s_cmpk_lt_i32 s78, 0x500
	s_cselect_b64 s[0:1], -1, 0
	v_writelane_b32 v254, s0, 3
	s_mov_b32 s95, 0
	v_mov_b32_e32 v209, 0x358637bd
	v_writelane_b32 v254, s1, 4
	s_lshr_b32 s0, s79, 29
	s_add_i32 s0, s78, s0
	s_ashr_i32 s1, s0, 3
	s_and_b32 s0, s0, -8
	s_sub_i32 s3, s78, s0
	s_add_u32 s38, s10, 0x1ce00200
	s_addc_u32 s39, s11, 0
	s_add_u32 s4, s10, 0x1ce03400
	s_addc_u32 s5, s11, 0
	s_add_u32 s40, s10, 0x1ce03500
	s_addc_u32 s41, s11, 0
	v_writelane_b32 v254, s4, 5
	s_cmpk_lt_i32 s78, 0x400
	s_mul_i32 s2, s3, 0x41
	v_writelane_b32 v254, s5, 6
	s_cselect_b64 s[4:5], -1, 0
	s_lshl_b32 s94, s78, 1
	v_writelane_b32 v254, s4, 7
	s_cmpk_lt_i32 s78, 0x200
	s_mov_b32 s68, 0x800000
	v_writelane_b32 v254, s5, 8
	s_cselect_b64 s[4:5], -1, 0
	v_writelane_b32 v254, s4, 9
	s_lshl_b32 s0, s78, 8
	s_lshl_b32 s42, s86, 8
	v_writelane_b32 v254, s5, 10
	v_writelane_b32 v254, s0, 11
	s_lshl_b32 s0, s3, 6
	s_cmpk_lt_i32 s78, 0xb00
	s_cselect_b64 s[4:5], -1, 0
	v_writelane_b32 v254, s4, 12
	s_cmp_lt_i32 s3, 0
	s_cselect_b32 s2, s2, s0
	v_writelane_b32 v254, s5, 13
	s_movk_i32 s4, 0xa1
	s_cselect_b32 s4, s4, 0xa0
	s_mul_i32 s4, s3, s4
	s_movk_i32 s0, 0x161
	s_cselect_b32 s5, s0, 0x160
	s_add_i32 s4, s4, s1
	s_mul_hi_i32 s0, s4, 0x66666667
	s_lshr_b32 s6, s0, 31
	s_ashr_i32 s0, s0, 5
	s_add_i32 s0, s0, s6
	s_mul_i32 s6, s0, 0x50
	s_sub_i32 s4, s4, s6
	s_lshl_b32 s7, s0, 3
	s_bfe_i32 s0, s4, 0x80000
	s_bfe_u32 s0, s0, 0x3000c
	s_add_i32 s6, s4, s0
	s_bfe_i32 s0, s6, 0x80000
	s_and_b32 s6, s6, 0xf8
	s_sub_i32 s4, s4, s6
	s_sext_i32_i16 s8, s0
	s_sext_i32_i8 s4, s4
	s_add_i32 s10, s7, s4
	s_ashr_i32 s4, s8, 3
	s_add_i32 s2, s2, s1
	v_writelane_b32 v254, s4, 14
	s_ashr_i32 s4, s2, 31
	s_lshr_b32 s4, s4, 27
	s_add_i32 s4, s2, s4
	s_ashr_i32 s6, s4, 5
	s_and_b32 s4, s4, 0xffe0
	s_sub_i32 s4, s2, s4
	s_bfe_i32 s2, s4, 0x80000
	s_bfe_u32 s2, s2, 0x3000c
	s_add_i32 s7, s4, s2
	s_bfe_i32 s2, s7, 0x80000
	s_and_b32 s7, s7, 0xf8
	s_mul_i32 s3, s3, s5
	s_sub_i32 s4, s4, s7
	s_add_i32 s3, s3, s1
	s_lshl_b32 s6, s6, 3
	s_sext_i32_i8 s4, s4
	s_mul_hi_i32 s1, s3, 0x2e8ba2e9
	s_add_i32 s12, s6, s4
	s_lshr_b32 s4, s1, 31
	s_ashr_i32 s1, s1, 5
	s_add_i32 s1, s1, s4
	s_lshl_b32 s5, s1, 3
	s_mulk_i32 s1, 0xb0
	s_sub_i32 s1, s3, s1
	s_bfe_u32 s3, s1, 0x3001c
	s_add_i32 s3, s1, s3
	s_sext_i32_i16 s6, s3
	s_and_b32 s3, s3, 0xfff8
	s_sub_i32 s1, s1, s3
	s_lshr_b32 s0, s8, 3
	s_sext_i32_i16 s8, s2
	s_sext_i32_i16 s1, s1
	s_lshr_b32 s2, s8, 3
	s_ashr_i32 s7, s8, 3
	s_add_i32 s8, s5, s1
	s_ashr_i32 s1, s6, 3
	v_writelane_b32 v254, s1, 15
	s_mul_hi_i32 s1, s12, 0x160000
	v_writelane_b32 v254, s1, 16
	s_mul_i32 s1, s12, 0x160000
	v_writelane_b32 v254, s1, 17
	s_mul_hi_i32 s1, s7, 0x160000
	v_writelane_b32 v254, s1, 18
	v_writelane_b32 v254, s7, 19
	s_mul_i32 s1, s7, 0x160000
	s_lshr_b32 s4, s6, 3
	v_writelane_b32 v254, s1, 20
	s_mov_b32 s6, s10
	s_ashr_i32 s11, s10, 31
	v_writelane_b32 v254, s6, 21
	s_bfe_i64 s[0:1], s[0:1], 0x100000
	s_lshl_b64 s[0:1], s[0:1], 19
	v_writelane_b32 v254, s7, 22
	s_lshl_b64 s[6:7], s[10:11], 19
	v_writelane_b32 v254, s6, 23
	s_ashr_i32 s13, s12, 31
	s_bfe_i64 s[2:3], s[2:3], 0x100000
	v_writelane_b32 v254, s7, 24
	v_writelane_b32 v254, s0, 25
	s_ashr_i32 s9, s8, 31
	s_mov_b32 s6, s86
	v_writelane_b32 v254, s1, 26
	s_mov_b32 s0, s12
	v_writelane_b32 v254, s0, 27
	v_mov_b32_e32 v2, 0
	s_movk_i32 s62, 0x1200
	v_writelane_b32 v254, s1, 28
	s_lshl_b64 s[0:1], s[12:13], 19
	v_writelane_b32 v254, s0, 29
	v_mov_b32_e32 v210, 1
	s_mov_b32 s65, 0x3fb8aa3b
	v_writelane_b32 v254, s1, 30
	s_lshl_b64 s[0:1], s[2:3], 19
	v_writelane_b32 v254, s0, 31
	v_mov_b32_e32 v156, 0x43030000
	v_mbcnt_hi_u32_b32 v211, -1, v10
	v_writelane_b32 v254, s1, 32
	s_mov_b32 s0, s8
	v_writelane_b32 v254, s0, 33
	v_mov_b64_e32 v[168:169], 0x4ff
	v_mov_b64_e32 v[248:249], 0x500
	v_writelane_b32 v254, s1, 34
	s_lshl_b64 s[0:1], s[8:9], 19
	v_writelane_b32 v254, s0, 35
	v_mov_b32_e32 v212, 0x41b17218
	v_mov_b32_e32 v213, 32
	v_writelane_b32 v254, s1, 36
	s_bfe_i64 s[0:1], s[4:5], 0x100000
	s_lshl_b64 s[0:1], s[0:1], 19
	v_writelane_b32 v254, s0, 37
	v_mov_b32_e32 v214, 63
	v_mov_b32_e32 v215, 0x42800000
	v_writelane_b32 v254, s1, 38
	s_add_i32 s0, s78, s86
	s_lshl_b32 s1, s0, 7
	v_writelane_b32 v254, s1, 39
	s_lshl_b32 s1, s86, 7
	v_writelane_b32 v254, s1, 40
	s_lshl_b32 s1, s0, 5
	v_writelane_b32 v254, s1, 41
	s_lshl_b32 s1, s86, 5
	v_writelane_b32 v254, s1, 42
	s_lshl_b32 s0, s0, 1
	v_writelane_b32 v254, s0, 43
	s_lshl_b32 s0, s86, 1
	s_bitcmp1_b32 s78, 0
	v_writelane_b32 v254, s0, 44
	s_cselect_b64 s[0:1], -1, 0
	v_writelane_b32 v254, s0, 45
	s_bitcmp1_b32 s86, 0
	v_mov_b32_e32 v216, 0xff800000
	v_writelane_b32 v254, s1, 46
	s_cselect_b64 s[0:1], -1, 0
	v_writelane_b32 v254, s0, 47
	v_mov_b32_e32 v217, 5
	v_mov_b32_e32 v218, 31
	v_writelane_b32 v254, s1, 48
	s_lshl_b32 s0, s78, 7
	v_writelane_b32 v254, s0, 49
	s_lshl_b32 s0, s78, 5
	v_writelane_b32 v254, s0, 50
	s_add_i32 s0, 0, 0x23800
	v_writelane_b32 v254, s0, 51
	s_add_i32 s0, 0, 0x22400
	v_writelane_b32 v254, s0, 52
	s_add_i32 s0, 0, 0x22404
	v_writelane_b32 v254, s0, 53
	v_writelane_b32 v254, s78, 54
	v_mov_b64_e32 v[162:163], 0x200
	v_mov_b64_e32 v[164:165], 0x1ff
	v_writelane_b32 v254, s79, 55
	v_writelane_b32 v254, s84, 56
	v_mov_b64_e32 v[166:167], 0xaff
	v_mov_b64_e32 v[250:251], 0xb00
	v_writelane_b32 v254, s85, 57
	v_writelane_b32 v254, s6, 58
	s_mov_b32 s57, 0x42fc0000
	s_mov_b32 s0, 0x42040000
	v_writelane_b32 v254, s7, 59
	v_writelane_b32 v254, s92, 60
	s_mov_b32 s33, 0x42080000
	s_mov_b32 s61, 0x420c0000
	v_writelane_b32 v254, s93, 61
	v_writelane_b32 v254, s87, 62
	v_writelane_b32 v254, s38, 63
	s_mov_b32 s4, 0x42400000
	s_mov_b32 s81, 0x42440000
	v_writelane_b32 v253, s39, 0
	v_writelane_b32 v253, s40, 1
	s_mov_b32 s69, 0x42480000
	s_mov_b32 s59, 0x424c0000
	v_writelane_b32 v253, s41, 2
	s_mov_b32 s58, 0x42820000
	s_mov_b32 s64, 0x42840000
	s_mov_b32 s3, 0x42860000
	s_mov_b32 s2, 0x42a00000
	s_mov_b32 s63, 0x42a20000
	s_mov_b32 s82, 0x42a40000
	s_mov_b32 s83, 0x42a60000
	s_mov_b32 s80, 0x42c00000
	s_mov_b32 s90, 0x42c20000
	s_mov_b32 s91, 0x42c40000
	s_mov_b32 s88, 0x42c60000
	s_mov_b32 s89, 0x42e00000
	s_mov_b32 s75, 0x42e20000
	s_mov_b32 s96, 0x42e40000
	s_mov_b32 s97, 0x42e60000
	s_mov_b32 s5, 0x43000000
	s_mov_b32 s60, 0x43010000
	s_mov_b32 s66, 0x43020000
	s_mov_b32 s67, 0xffffff8
	s_mov_b32 s74, 0x7e00000
	s_movk_i32 s1, 0x5800
	s_mov_b64 s[20:21], -1
	s_mov_b64 s[76:77], 0x80
	s_mov_b32 s36, s95
	v_writelane_b32 v253, s94, 3
	s_waitcnt lgkmcnt(0)
	s_barrier
	v_readfirstlane_b32 s99, v208
	s_cmp_ge_u32 s99, 64
	s_cbranch_scc1 .Lxl_chk_done
	v_mbcnt_lo_u32_b32 v124, -1, 0
	v_and_b32_e32 v126, 7, v124
	v_lshlrev_b32_e32 v126, 2, v126
	global_load_dword v126, v126, s[92:93] sc1
	s_waitcnt vmcnt(0)
	v_add_u32_e32 v127, -1, v126
	v_and_b32_e32 v127, v127, v126
	v_cmp_eq_u32_e32 vcc, 0, v126
	v_cndmask_b32_e64 v128, 0, 1, vcc
	v_or_b32_e32 v127, v127, v128
	v_cmp_ne_u32_e32 vcc, 0, v127
	s_cmp_eq_u64 vcc, 0
	s_cselect_b32 s99, 1, 0
	s_cmp_eq_u32 s86, 0x100
	s_cselect_b32 s99, s99, 0
.Lxl_chk_done:
	v_writelane_b32 v253, s42, 4
	s_branch .LBB0_133

.LBB0_628:
	s_mov_b32 s6, s73
	s_waitcnt vmcnt(0)
	s_waitcnt lgkmcnt(0)
	s_barrier
	s_and_saveexec_b64 s[8:9], s[30:31]
	s_cbranch_execz .LBB0_665
	s_cmp_eq_u32 s99, 0
	s_cbranch_scc1 .Lxl5_grid
	v_readlane_b32 s7, v254, 52
	s_lshl_b32 s10, s6, 8
	s_add_i32 s10, s10, 0x3800
	s_add_u32 s10, s92, s10
	s_addc_u32 s11, s93, 0
	v_mov_b32_e32 v0, s7
	ds_read_b32 v3, v0
	v_mov_b32_e32 v5, 0
	v_mov_b32_e32 v4, 1
	buffer_inv sc1
	global_atomic_add v4, v5, v4, s[10:11] sc0
	s_movk_i32 s7, 0x4000
	s_waitcnt lgkmcnt(0)
	v_mul_lo_u32 v7, v3, s99
	s_waitcnt vmcnt(0)
	v_add_u32_e32 v4, 1, v4
	v_cmp_ge_u32_e32 vcc, v4, v7
	s_cbranch_vccnz .Lxl5_done
.Lxl5_poll:
	s_sleep 1
	global_load_dword v0, v5, s[10:11] sc1
	s_sub_i32 s7, s7, 1
	s_cmp_eq_u32 s7, 0
	s_cbranch_scc1 .Lxl5_done
	s_waitcnt vmcnt(0)
	v_cmp_lt_u32_e32 vcc, v0, v7
	s_cbranch_vccnz .Lxl5_poll
.Lxl5_done:
	s_waitcnt vmcnt(0)
	s_add_i32 s99, s99, 1
	s_branch .LBB0_665
.Lxl5_grid:
	v_readlane_b32 s7, v254, 52
	s_waitcnt vmcnt(0) expcnt(0) lgkmcnt(0)
	s_mov_b64 s[10:11], exec
	v_mov_b32_e32 v0, s7
	v_readlane_b32 s7, v254, 53
	ds_read_b32 v3, v0
	v_mbcnt_lo_u32_b32 v1, s10, 0
	v_mov_b32_e32 v0, s7
	ds_read_b32 v0, v0
	v_mbcnt_hi_u32_b32 v1, s11, v1
	s_lshl_b32 s6, s6, 6
	v_cmp_eq_u32_e32 vcc, 0, v1
	s_and_saveexec_b64 s[12:13], vcc
	s_cbranch_execz .LBB0_631
	s_add_i32 s94, s6, 0x500
	s_lshl_b64 s[14:15], s[94:95], 2
	s_add_u32 s14, s92, s14
	s_addc_u32 s15, s93, s15
	s_bcnt1_i32_b64 s7, s[10:11]
	v_mov_b32_e32 v4, s7
	global_atomic_add v4, v2, v4, s[14:15] sc0
	v_readlane_b32 s94, v253, 3
	v_readlane_b32 s87, v254, 62

	.amdhsa_kernel _Z9hymba_fwd4Args
		.amdhsa_group_segment_fixed_size 0
		.amdhsa_private_segment_fixed_size 0
		.amdhsa_kernarg_size 392
		.amdhsa_user_sgpr_count 2
		.amdhsa_user_sgpr_dispatch_ptr 0
		.amdhsa_user_sgpr_queue_ptr 0
		.amdhsa_user_sgpr_kernarg_segment_ptr 1
		.amdhsa_user_sgpr_dispatch_id 0
		.amdhsa_user_sgpr_kernarg_preload_length 0
		.amdhsa_user_sgpr_kernarg_preload_offset 0
		.amdhsa_user_sgpr_private_segment_size 0
		.amdhsa_uses_dynamic_stack 0
		.amdhsa_enable_private_segment 0
		.amdhsa_system_sgpr_workgroup_id_x 1
		.amdhsa_system_sgpr_workgroup_id_y 0
		.amdhsa_system_sgpr_workgroup_id_z 0
		.amdhsa_system_sgpr_workgroup_info 0
		.amdhsa_system_vgpr_workitem_id 2
		.amdhsa_next_free_vgpr 255
		.amdhsa_next_free_sgpr 100
		.amdhsa_accum_offset 256
		.amdhsa_reserve_vcc 1
		.amdhsa_float_round_mode_32 0
		.amdhsa_float_round_mode_16_64 0
		.amdhsa_float_denorm_mode_32 3
		.amdhsa_float_denorm_mode_16_64 3
		.amdhsa_dx10_clamp 1
		.amdhsa_ieee_mode 1
		.amdhsa_fp16_overflow 0
		.amdhsa_tg_split 0
		.amdhsa_exception_fp_ieee_invalid_op 0
		.amdhsa_exception_fp_denorm_src 0
		.amdhsa_exception_fp_ieee_div_zero 0
		.amdhsa_exception_fp_ieee_overflow 0
		.amdhsa_exception_fp_ieee_underflow 0
		.amdhsa_exception_fp_ieee_inexact 0
		.amdhsa_exception_int_div_zero 0
	.end_amdhsa_kernel

amdhsa.kernels:
  - .agpr_count:     0
    .args:
      - .offset:         0
        .size:           136
        .value_kind:     by_value
      - .offset:         136
        .size:           4
        .value_kind:     hidden_block_count_x
      - .offset:         140
        .size:           4
        .value_kind:     hidden_block_count_y
      - .offset:         144
        .size:           4
        .value_kind:     hidden_block_count_z
      - .offset:         148
        .size:           2
        .value_kind:     hidden_group_size_x
      - .offset:         150
        .size:           2
        .value_kind:     hidden_group_size_y
      - .offset:         152
        .size:           2
        .value_kind:     hidden_group_size_z
      - .offset:         154
        .size:           2
        .value_kind:     hidden_remainder_x
      - .offset:         156
        .size:           2
        .value_kind:     hidden_remainder_y
      - .offset:         158
        .size:           2
        .value_kind:     hidden_remainder_z
      - .offset:         176
        .size:           8
        .value_kind:     hidden_global_offset_x
      - .offset:         184
        .size:           8
        .value_kind:     hidden_global_offset_y
      - .offset:         192
        .size:           8
        .value_kind:     hidden_global_offset_z
      - .offset:         200
        .size:           2
        .value_kind:     hidden_grid_dims
      - .offset:         224
        .size:           8
        .value_kind:     hidden_multigrid_sync_arg
      - .offset:         256
        .size:           4
        .value_kind:     hidden_dynamic_lds_size
    .group_segment_fixed_size: 0
    .kernarg_segment_align: 8
    .kernarg_segment_size: 392
    .language:       OpenCL C
    .language_version:
      - 2
      - 0
    .max_flat_workgroup_size: 512
    .name:           _Z9hymba_fwd4Args
    .private_segment_fixed_size: 0
    .sgpr_count:     106
    .sgpr_spill_count: 99
    .symbol:         _Z9hymba_fwd4Args.kd
    .uniform_work_group_size: 1
    .uses_dynamic_stack: false
    .vgpr_count:     255
    .vgpr_spill_count: 0
    .wavefront_size: 64
